# v21: v20 + P0 third transpose items moved to 8-row waves + P11 epilogue rsqrt denormal guards removed (7 sites, same f32 math)
# speedup vs baseline: 1.0013x; 1.0013x over previous
; __global__ void __launch_bounds__(512, 2) mega_fwd(Args args) {
;     ...
;         for (int it = gw; it < NIT; it += NGW) {
;             int r = it;
;             if (r < I_IN) { transpose_mat(w_in, D, INW, WT_IN, 0, 0, nullptr, nullptr, r, scr, lane); continue; } r -= I_IN;
;             if (r < I_OUT) { transpose_mat(w_out, D, D, WT_OUT, 0, 0, nullptr, nullptr, r, scr, lane); continue; } r -= I_OUT;
;             if (r < I_MQ) { transpose_mat(w_mem_q, D, MEMW, WT_MQ, 0, 0, nullptr, norm_mem, r, scr, lane); continue; } r -= I_MQ;
;             if (r < I_MQ) { transpose_mat(w_mem_k, D, MEMW, WT_MKV, 0, 0, nullptr, nullptr, r, scr, lane); continue; } r -= I_MQ;
;             if (r < I_MQ) { transpose_mat(w_mem_v, D, MEMW, WT_MKV, 0, 512, nullptr, nullptr, r, scr, lane); continue; } r -= I_MQ;
;             if (r < I_MO) { transpose_mat(w_mem_o, MEMW, D, WT_MO, 0, 0, nullptr, nullptr, r, scr, lane); continue; } r -= I_MO;
;             { const int g = r / I_PL; transpose_mat(w_pool + (size_t)g * 65536, 256, 256, WT_POOL, 0, g * 256, pool_scale, nullptr, r % I_PL, scr, lane); }
;         }
.LBB0_8:
	s_add_i32 s79, s79, s14
	s_cmpk_lt_i32 s79, 0x1000
	s_cbranch_scc1 .Lp0_norm
	s_sub_i32 s79, 0x27ff, s79
	s_cmpk_lt_i32 s79, 0x1000
	s_cbranch_scc1 .LBB0_65
.Lp0_norm:
	s_lshl_b32 s13, s79, 6
	s_lshl_b32 s27, s79, 4
	s_lshl_b32 s41, s79, 1
	s_lshl_b32 s49, s79, 3
	s_cmpk_gt_i32 s79, 0x103f
	s_cbranch_scc1 .LBB0_65

; __device__ __forceinline__ unsigned pk2(float lo, float hi) { f32x2_t v = {lo, hi}; bf16x2_t b = __builtin_convertvector(v, bf16x2_t); return __builtin_bit_cast(unsigned, b); }
; __device__ __forceinline__ float dpp_ror1(float x) { return __int_as_float(__builtin_amdgcn_update_dpp(0, __float_as_int(x), 0x121, 0xf, 0xf, false)); }
; __device__ __forceinline__ float dpp_ror2(float x) { return __int_as_float(__builtin_amdgcn_update_dpp(0, __float_as_int(x), 0x122, 0xf, 0xf, false)); }
;     __device__ __forceinline__ float rsq(int row) const { const f32x4 q0 = *(const f32x4*)(pssq + (size_t)row * 8), q1 = *(const f32x4*)(pssq + (size_t)row * 8 + 4);
;         return rsqrtf(((q0.x + q0.y) + (q0.z + q0.w) + (q1.x + q1.y) + (q1.z + q1.w)) * (1.f / D) + EPS); }
;     __device__ __forceinline__ void operator()(const f32x4 (&acc)[2][2][4][2], const Unit& u, int wr, int wc, int fr, int fq) const {
;     ...
;             for (int m = 0; m < 4; ++m) { const int row = rowb + ai * HALF + m * 16; const float rs = rsq(row);
;                 f32x4 g[2], a[2];
; #pragma unroll
;                 for (int n = 0; n < 2; ++n) { g[n] = acc[ai][0][m][n] * rs; const f32x4 up = acc[ai][1][m][n] * rs;
; #pragma unroll
;                     for (int e = 0; e < 4; ++e) { const float r1c = dpp_ror1(g[n][e]), r1p = dpp_ror1(gprev[n][e]), r2c = dpp_ror2(g[n][e]), r2p = dpp_ror2(gprev[n][e]);
;                         const float p1 = fr >= 1 ? r1c : r1p, p2 = fr >= 2 ? r2c : r2p;
;                         const float c = bb[n][e] + w0[n][e] * p2 + w1[n][e] * p1 + w2[n][e] * g[n][e]; a[n][e] = c / (1.f + __expf(-c)) * up[e]; }
;                     if (ai == 0 && m == 0 && wr == 0 && fr < 2) { *(f32x4*)(firstg + ((size_t)u.pm * 2 + fr) * FF + ch0 + 4 * n) = g[n]; *(f32x4*)(firstup + ((size_t)u.pm * 2 + fr) * FF + ch0 + 4 * n) = up; }
;                     if (ai == 1 && m == 3 && wr == 1 && fr >= 14) *(f32x4*)(lastg + ((size_t)u.pm * 2 + (fr - 14)) * FF + ch0 + 4 * n) = g[n]; }
;                 if (!(ai == 0 && m == 0 && wr == 0 && fr < 2)) { u32x4 w; w.x = pk2(a[0][0], a[0][1]); w.y = pk2(a[0][2], a[0][3]); w.z = pk2(a[1][0], a[1][1]); w.w = pk2(a[1][2], a[1][3]);
;                     *(u32x4*)(ACT + (size_t)row * FF + ch0) = w; }
.LBB0_799:
	s_or_b64 exec, exec, s[18:19]
	s_nop 0
	v_or_b32_e32 v144, 16, v184
	v_ashrrev_i32_e32 v145, 31, v144
	v_lshlrev_b64 v[146:147], 5, v[144:145]
	v_lshl_add_u64 v[146:147], s[46:47], 0, v[146:147]
	global_load_dwordx4 v[152:155], v[146:147], off
	global_load_dwordx4 v[188:191], v[146:147], off offset:16
	v_mov_b32_dpp v199, v156 row_ror:2 row_mask:0xf bank_mask:0xf
	v_mov_b32_dpp v215, v157 row_ror:2 row_mask:0xf bank_mask:0xf
	v_mov_b32_dpp v185, v156 row_ror:1 row_mask:0xf bank_mask:0xf
	v_mov_b32_dpp v213, v157 row_ror:1 row_mask:0xf bank_mask:0xf
	v_mov_b32_dpp v219, v158 row_ror:2 row_mask:0xf bank_mask:0xf
	v_mov_b32_dpp v223, v159 row_ror:2 row_mask:0xf bank_mask:0xf
	v_mov_b32_dpp v217, v158 row_ror:1 row_mask:0xf bank_mask:0xf
	v_mov_b32_dpp v221, v159 row_ror:1 row_mask:0xf bank_mask:0xf
	s_waitcnt vmcnt(1)
	v_mov_b32_e32 v146, v153
	v_mov_b32_e32 v147, v154
	v_mov_b32_e32 v153, v155
	s_waitcnt vmcnt(0)
	v_mov_b32_e32 v154, v190
	v_mov_b32_e32 v155, v188
	v_mov_b32_e32 v188, v191
	v_pk_add_f32 v[146:147], v[146:147], v[152:153]
	v_pk_add_f32 v[152:153], v[154:155], v[188:189]
	v_add_f32_e32 v146, v146, v147
	v_add_f32_e32 v146, v146, v153
	v_add_f32_e32 v146, v152, v146
	v_fmamk_f32 v146, v146, 0x3a000000, v178
	s_nop 1
	v_rsq_f32_e32 v146, v146
	s_nop 0
	v_pk_mul_f32 v[140:141], v[140:141], v[146:147] op_sel_hi:[1,0]
	v_pk_mul_f32 v[142:143], v[142:143], v[146:147] op_sel_hi:[1,0]
	s_nop 0
	v_mov_b32_dpp v198, v140 row_ror:2 row_mask:0xf bank_mask:0xf
	v_mov_b32_dpp v214, v141 row_ror:2 row_mask:0xf bank_mask:0xf
	v_mov_b32_dpp v145, v140 row_ror:1 row_mask:0xf bank_mask:0xf
	v_mov_b32_dpp v212, v141 row_ror:1 row_mask:0xf bank_mask:0xf
	v_cndmask_b32_e64 v155, v215, v214, s[8:9]
	v_cndmask_b32_e64 v154, v199, v198, s[8:9]
	v_cndmask_b32_e64 v153, v212, v213, s[6:7]
	v_cndmask_b32_e64 v152, v145, v185, s[6:7]
	v_pk_fma_f32 v[154:155], v[44:45], v[154:155], v[52:53]
	v_mov_b32_dpp v218, v142 row_ror:2 row_mask:0xf bank_mask:0xf
	v_pk_fma_f32 v[152:153], v[40:41], v[152:153], v[154:155]
	v_mov_b32_dpp v222, v143 row_ror:2 row_mask:0xf bank_mask:0xf
	v_pk_fma_f32 v[140:141], v[48:49], v[140:141], v[152:153]
	v_mov_b32_dpp v216, v142 row_ror:1 row_mask:0xf bank_mask:0xf
	v_mul_f32_e32 v147, 0xbfb8aa3b, v140
	v_mul_f32_e32 v153, 0xbfb8aa3b, v141
	v_exp_f32_e32 v152, v147
	v_exp_f32_e32 v153, v153
	v_mov_b32_dpp v220, v143 row_ror:1 row_mask:0xf bank_mask:0xf
	v_cndmask_b32_e64 v159, v223, v222, s[8:9]
	v_cndmask_b32_e64 v158, v219, v218, s[8:9]
	v_cndmask_b32_e64 v157, v220, v221, s[6:7]
	v_cndmask_b32_e64 v156, v216, v217, s[6:7]
	v_pk_fma_f32 v[158:159], v[46:47], v[158:159], v[54:55]
	v_pk_add_f32 v[152:153], v[152:153], 1.0 op_sel_hi:[1,0]
	v_pk_fma_f32 v[154:155], v[42:43], v[156:157], v[158:159]
	v_pk_mul_f32 v[138:139], v[138:139], v[146:147] op_sel_hi:[1,0]
	v_pk_fma_f32 v[142:143], v[50:51], v[142:143], v[154:155]
	v_pk_mul_f32 v[136:137], v[136:137], v[146:147] op_sel_hi:[1,0]
	v_mul_f32_e32 v154, 0xbfb8aa3b, v142
	v_mul_f32_e32 v155, 0xbfb8aa3b, v143
	v_rcp_f32_e32 v185, v153
	v_exp_f32_e32 v154, v154
	v_exp_f32_e32 v155, v155
	v_rcp_f32_e32 v188, v152
	v_pk_add_f32 v[154:155], v[154:155], 1.0 op_sel_hi:[1,0]
	v_rcp_f32_e32 v189, v155
	v_mul_f32_e32 v141, v141, v185
	v_mul_f32_e32 v140, v140, v188
	v_pk_mul_f32 v[136:137], v[136:137], v[140:141]
	v_rcp_f32_e32 v147, v154
	v_mul_f32_e32 v141, v143, v189
	v_pk_mul_f32 v[132:133], v[132:133], v[146:147] op_sel_hi:[1,0]
	v_mov_b32_dpp v143, v148 row_ror:1 row_mask:0xf bank_mask:0xf
	s_nop 0
	v_mov_b32_dpp v157, v132 row_ror:2 row_mask:0xf bank_mask:0xf
	v_mov_b32_dpp v152, v148 row_ror:2 row_mask:0xf bank_mask:0xf
	v_mov_b32_dpp v159, v133 row_ror:2 row_mask:0xf bank_mask:0xf
	v_mov_b32_dpp v153, v149 row_ror:2 row_mask:0xf bank_mask:0xf
	v_mov_b32_dpp v156, v132 row_ror:1 row_mask:0xf bank_mask:0xf
	v_mov_b32_dpp v158, v133 row_ror:1 row_mask:0xf bank_mask:0xf
	v_mov_b32_dpp v148, v149 row_ror:1 row_mask:0xf bank_mask:0xf
	v_cndmask_b32_e64 v153, v153, v159, s[8:9]
	v_cndmask_b32_e64 v152, v152, v157, s[8:9]
	v_cndmask_b32_e64 v149, v158, v148, s[6:7]
	v_cndmask_b32_e64 v148, v156, v143, s[6:7]
	v_pk_fma_f32 v[152:153], v[72:73], v[152:153], v[76:77]
	v_pk_fma_f32 v[148:149], v[64:65], v[148:149], v[152:153]
	v_mul_f32_e32 v140, v142, v147
	v_pk_fma_f32 v[132:133], v[68:69], v[132:133], v[148:149]
	v_pk_mul_f32 v[138:139], v[138:139], v[140:141]
	v_mul_f32_e32 v143, 0xbfb8aa3b, v132
	v_exp_f32_e32 v148, v143
	v_mul_f32_e32 v143, 0xbfb8aa3b, v133
	v_exp_f32_e32 v149, v143
	v_pk_mul_f32 v[134:135], v[134:135], v[146:147] op_sel_hi:[1,0]
	v_pk_mul_f32 v[130:131], v[130:131], v[146:147] op_sel_hi:[1,0]
	v_pk_mul_f32 v[128:129], v[128:129], v[146:147] op_sel_hi:[1,0]
	v_pk_add_f32 v[140:141], v[148:149], 1.0 op_sel_hi:[1,0]
	v_rcp_f32_e32 v143, v141
	v_mov_b32_dpp v154, v134 row_ror:2 row_mask:0xf bank_mask:0xf
	v_mul_f32_e32 v133, v133, v143
	v_mov_b32_dpp v142, v150 row_ror:1 row_mask:0xf bank_mask:0xf
	v_mov_b32_dpp v146, v150 row_ror:2 row_mask:0xf bank_mask:0xf
	v_mov_b32_dpp v155, v135 row_ror:2 row_mask:0xf bank_mask:0xf
	v_mov_b32_dpp v147, v151 row_ror:2 row_mask:0xf bank_mask:0xf
	v_mov_b32_dpp v153, v134 row_ror:1 row_mask:0xf bank_mask:0xf
	v_mov_b32_dpp v150, v135 row_ror:1 row_mask:0xf bank_mask:0xf
	v_mov_b32_dpp v143, v151 row_ror:1 row_mask:0xf bank_mask:0xf
	v_cndmask_b32_e64 v147, v147, v155, s[8:9]
	v_cndmask_b32_e64 v146, v146, v154, s[8:9]
	v_cndmask_b32_e64 v143, v150, v143, s[6:7]
	v_cndmask_b32_e64 v142, v153, v142, s[6:7]
	v_pk_fma_f32 v[146:147], v[74:75], v[146:147], v[78:79]
	v_rcp_f32_e32 v149, v140
	v_pk_fma_f32 v[142:143], v[66:67], v[142:143], v[146:147]
	v_pk_fma_f32 v[134:135], v[70:71], v[134:135], v[142:143]
	v_mul_f32_e32 v142, 0xbfb8aa3b, v134
	v_mul_f32_e32 v143, 0xbfb8aa3b, v135
	v_exp_f32_e32 v142, v142
	v_exp_f32_e32 v143, v143
	s_nop 0
	v_pk_add_f32 v[142:143], v[142:143], 1.0 op_sel_hi:[1,0]
	v_rcp_f32_e32 v147, v143
	v_mul_f32_e32 v132, v132, v149
	v_pk_mul_f32 v[128:129], v[128:129], v[132:133]
	v_rcp_f32_e32 v141, v142
	v_mul_f32_e32 v133, v135, v147
	v_mul_f32_e32 v132, v134, v141
	v_pk_mul_f32 v[130:131], v[130:131], v[132:133]
	v_cvt_pk_bf16_f32 v134, v128, v129
	v_mov_b64_e32 v[128:129], s[44:45]
	v_cvt_pk_bf16_f32 v132, v136, v137
	v_cvt_pk_bf16_f32 v135, v130, v131
	v_mad_i64_i32 v[136:137], s[16:17], v144, s33, v[128:129]
	v_lshlrev_b64 v[130:131], 1, v[180:181]
	v_cvt_pk_bf16_f32 v133, v138, v139
	v_lshl_add_u64 v[136:137], v[136:137], 0, v[130:131]
	global_store_dwordx4 v[136:137], v[132:135], off
	s_nop 1
	v_or_b32_e32 v132, 32, v184
	s_nop 0
	v_ashrrev_i32_e32 v133, 31, v132
	v_lshlrev_b64 v[134:135], 5, v[132:133]
	v_lshl_add_u64 v[138:139], s[46:47], 0, v[134:135]
	global_load_dwordx4 v[134:137], v[138:139], off
	s_nop 0
	global_load_dwordx4 v[138:141], v[138:139], off offset:16
	s_waitcnt vmcnt(1)
; __device__ __forceinline__ unsigned pk2(float lo, float hi) { f32x2_t v = {lo, hi}; bf16x2_t b = __builtin_convertvector(v, bf16x2_t); return __builtin_bit_cast(unsigned, b); }
; __device__ __forceinline__ float dpp_ror1(float x) { return __int_as_float(__builtin_amdgcn_update_dpp(0, __float_as_int(x), 0x121, 0xf, 0xf, false)); }
; __device__ __forceinline__ float dpp_ror2(float x) { return __int_as_float(__builtin_amdgcn_update_dpp(0, __float_as_int(x), 0x122, 0xf, 0xf, false)); }
;     __device__ __forceinline__ float rsq(int row) const { const f32x4 q0 = *(const f32x4*)(pssq + (size_t)row * 8), q1 = *(const f32x4*)(pssq + (size_t)row * 8 + 4);
;         return rsqrtf(((q0.x + q0.y) + (q0.z + q0.w) + (q1.x + q1.y) + (q1.z + q1.w)) * (1.f / D) + EPS); }
;     __device__ __forceinline__ void operator()(const f32x4 (&acc)[2][2][4][2], const Unit& u, int wr, int wc, int fr, int fq) const {
;     ...
;             for (int m = 0; m < 4; ++m) { const int row = rowb + ai * HALF + m * 16; const float rs = rsq(row);
;                 f32x4 g[2], a[2];
; #pragma unroll
;                 for (int n = 0; n < 2; ++n) { g[n] = acc[ai][0][m][n] * rs; const f32x4 up = acc[ai][1][m][n] * rs;
; #pragma unroll
;                     for (int e = 0; e < 4; ++e) { const float r1c = dpp_ror1(g[n][e]), r1p = dpp_ror1(gprev[n][e]), r2c = dpp_ror2(g[n][e]), r2p = dpp_ror2(gprev[n][e]);
;                         const float p1 = fr >= 1 ? r1c : r1p, p2 = fr >= 2 ? r2c : r2p;
;                         const float c = bb[n][e] + w0[n][e] * p2 + w1[n][e] * p1 + w2[n][e] * g[n][e]; a[n][e] = c / (1.f + __expf(-c)) * up[e]; }
;                     if (ai == 0 && m == 0 && wr == 0 && fr < 2) { *(f32x4*)(firstg + ((size_t)u.pm * 2 + fr) * FF + ch0 + 4 * n) = g[n]; *(f32x4*)(firstup + ((size_t)u.pm * 2 + fr) * FF + ch0 + 4 * n) = up; }
;                     if (ai == 1 && m == 3 && wr == 1 && fr >= 14) *(f32x4*)(lastg + ((size_t)u.pm * 2 + (fr - 14)) * FF + ch0 + 4 * n) = g[n]; }
;                 if (!(ai == 0 && m == 0 && wr == 0 && fr < 2)) { u32x4 w; w.x = pk2(a[0][0], a[0][1]); w.y = pk2(a[0][2], a[0][3]); w.z = pk2(a[1][0], a[1][1]); w.w = pk2(a[1][2], a[1][3]);
;                     *(u32x4*)(ACT + (size_t)row * FF + ch0) = w; }
	v_mov_b32_e32 v142, v135
	v_mov_b32_e32 v143, v136
	v_mov_b32_e32 v135, v137
	v_pk_add_f32 v[134:135], v[142:143], v[134:135]
	s_waitcnt vmcnt(0)
	v_mov_b32_e32 v136, v140
	v_mov_b32_e32 v137, v138
	v_mov_b32_e32 v138, v141
	v_pk_add_f32 v[136:137], v[136:137], v[138:139]
	v_add_f32_e32 v133, v134, v135
	v_add_f32_e32 v133, v133, v137
	v_add_f32_e32 v133, v136, v133
	v_fmamk_f32 v133, v133, 0x3a000000, v178
	s_nop 1
	v_rsq_f32_e32 v134, v133
	s_nop 0
	v_pk_mul_f32 v[124:125], v[124:125], v[134:135] op_sel_hi:[1,0]
	s_nop 0
	s_nop 0
	v_mov_b32_dpp v142, v124 row_ror:2 row_mask:0xf bank_mask:0xf
	v_mov_b32_dpp v144, v125 row_ror:2 row_mask:0xf bank_mask:0xf
	v_mov_b32_dpp v133, v124 row_ror:1 row_mask:0xf bank_mask:0xf
	v_mov_b32_dpp v143, v125 row_ror:1 row_mask:0xf bank_mask:0xf
	v_cndmask_b32_e64 v139, v214, v144, s[8:9]
	v_cndmask_b32_e64 v138, v198, v142, s[8:9]
	v_cndmask_b32_e64 v137, v143, v212, s[6:7]
	v_cndmask_b32_e64 v136, v133, v145, s[6:7]
	v_pk_fma_f32 v[138:139], v[44:45], v[138:139], v[52:53]
	s_nop 0
	v_pk_fma_f32 v[136:137], v[40:41], v[136:137], v[138:139]
	s_nop 0
	v_pk_fma_f32 v[124:125], v[48:49], v[124:125], v[136:137]
	s_nop 0
	v_mul_f32_e32 v135, 0xbfb8aa3b, v124
	v_exp_f32_e32 v136, v135
	v_mul_f32_e32 v135, 0xbfb8aa3b, v125
	v_exp_f32_e32 v137, v135
	s_nop 0
	v_pk_add_f32 v[136:137], v[136:137], 1.0 op_sel_hi:[1,0]
	s_nop 0
	v_rcp_f32_e32 v138, v137
	v_pk_mul_f32 v[126:127], v[126:127], v[134:135] op_sel_hi:[1,0]
	v_pk_mul_f32 v[122:123], v[122:123], v[134:135] op_sel_hi:[1,0]
	v_pk_mul_f32 v[120:121], v[120:121], v[134:135] op_sel_hi:[1,0]
	v_mov_b32_dpp v148, v126 row_ror:2 row_mask:0xf bank_mask:0xf
	v_mov_b32_dpp v151, v127 row_ror:2 row_mask:0xf bank_mask:0xf
	v_mul_f32_e32 v135, v125, v138
	v_mov_b32_dpp v147, v126 row_ror:1 row_mask:0xf bank_mask:0xf
	v_mov_b32_dpp v149, v127 row_ror:1 row_mask:0xf bank_mask:0xf
	v_cndmask_b32_e64 v141, v222, v151, s[8:9]
	v_cndmask_b32_e64 v140, v218, v148, s[8:9]
	v_cndmask_b32_e64 v139, v149, v220, s[6:7]
	v_cndmask_b32_e64 v138, v147, v216, s[6:7]
	v_pk_fma_f32 v[140:141], v[46:47], v[140:141], v[54:55]
	v_rcp_f32_e32 v146, v136
	v_pk_fma_f32 v[138:139], v[42:43], v[138:139], v[140:141]
	v_mov_b32_e32 v125, v135
	v_pk_fma_f32 v[126:127], v[50:51], v[126:127], v[138:139]
	v_mul_f32_e32 v138, 0xbfb8aa3b, v126
	v_mul_f32_e32 v139, 0xbfb8aa3b, v127
	v_exp_f32_e32 v138, v138
	v_exp_f32_e32 v139, v139
	s_nop 0
	v_pk_add_f32 v[138:139], v[138:139], 1.0 op_sel_hi:[1,0]
	v_rcp_f32_e32 v141, v139
	v_mul_f32_e32 v124, v124, v146
	v_pk_mul_f32 v[120:121], v[120:121], v[124:125]
	v_rcp_f32_e32 v145, v138
	v_mul_f32_e32 v125, v127, v141
	v_pk_mul_f32 v[116:117], v[116:117], v[134:135] op_sel_hi:[1,0]
	s_nop 0
	s_nop 0
	v_mov_b32_dpp v146, v116 row_ror:2 row_mask:0xf bank_mask:0xf
	v_mov_b32_dpp v185, v117 row_ror:2 row_mask:0xf bank_mask:0xf
	v_mov_b32_dpp v139, v116 row_ror:1 row_mask:0xf bank_mask:0xf
	v_mov_b32_dpp v152, v117 row_ror:1 row_mask:0xf bank_mask:0xf
	v_cndmask_b32_e64 v141, v159, v185, s[8:9]
	v_cndmask_b32_e64 v140, v157, v146, s[8:9]
	v_cndmask_b32_e64 v137, v152, v158, s[6:7]
	v_cndmask_b32_e64 v136, v139, v156, s[6:7]
	v_pk_fma_f32 v[140:141], v[72:73], v[140:141], v[76:77]
	v_pk_fma_f32 v[136:137], v[64:65], v[136:137], v[140:141]
	v_pk_fma_f32 v[116:117], v[68:69], v[116:117], v[136:137]
	v_mul_f32_e32 v124, v126, v145
	v_mul_f32_e32 v135, 0xbfb8aa3b, v116
	v_exp_f32_e32 v136, v135
	v_mul_f32_e32 v135, 0xbfb8aa3b, v117
	v_exp_f32_e32 v137, v135
	v_pk_mul_f32 v[122:123], v[122:123], v[124:125]
	v_pk_mul_f32 v[118:119], v[118:119], v[134:135] op_sel_hi:[1,0]
	v_pk_mul_f32 v[114:115], v[114:115], v[134:135] op_sel_hi:[1,0]
	v_pk_add_f32 v[124:125], v[136:137], 1.0 op_sel_hi:[1,0]
	v_pk_mul_f32 v[112:113], v[112:113], v[134:135] op_sel_hi:[1,0]
	v_rcp_f32_e32 v127, v125
	v_mov_b32_dpp v141, v118 row_ror:2 row_mask:0xf bank_mask:0xf
	v_mov_b32_dpp v156, v119 row_ror:2 row_mask:0xf bank_mask:0xf
	v_mov_b32_dpp v140, v118 row_ror:1 row_mask:0xf bank_mask:0xf
	v_mov_b32_dpp v145, v119 row_ror:1 row_mask:0xf bank_mask:0xf
	v_cndmask_b32_e64 v135, v155, v156, s[8:9]
	v_cndmask_b32_e64 v134, v154, v141, s[8:9]
	v_mul_f32_e32 v117, v117, v127
	v_cndmask_b32_e64 v127, v145, v150, s[6:7]
	v_cndmask_b32_e64 v126, v140, v153, s[6:7]
	v_pk_fma_f32 v[134:135], v[74:75], v[134:135], v[78:79]
	v_rcp_f32_e32 v137, v124
	v_pk_fma_f32 v[126:127], v[66:67], v[126:127], v[134:135]
	v_pk_fma_f32 v[118:119], v[70:71], v[118:119], v[126:127]
	v_mul_f32_e32 v126, 0xbfb8aa3b, v118
	v_mul_f32_e32 v127, 0xbfb8aa3b, v119
	v_exp_f32_e32 v126, v126
	v_exp_f32_e32 v127, v127
	s_nop 0
	v_pk_add_f32 v[126:127], v[126:127], 1.0 op_sel_hi:[1,0]
	v_rcp_f32_e32 v135, v127
	v_mul_f32_e32 v116, v116, v137
	v_pk_mul_f32 v[116:117], v[112:113], v[116:117]
	v_rcp_f32_e32 v125, v126
	v_mul_f32_e32 v113, v119, v135
	v_mul_f32_e32 v112, v118, v125
	v_pk_mul_f32 v[118:119], v[114:115], v[112:113]
	v_cvt_pk_bf16_f32 v114, v116, v117
	v_mad_i64_i32 v[116:117], s[16:17], v132, s33, v[128:129]
	v_cvt_pk_bf16_f32 v112, v120, v121
	v_cvt_pk_bf16_f32 v113, v122, v123
	v_cvt_pk_bf16_f32 v115, v118, v119
	v_lshl_add_u64 v[116:117], v[116:117], 0, v[130:131]
	global_store_dwordx4 v[116:117], v[112:115], off
	s_nop 1
	v_lshlrev_b64 v[112:113], 5, v[186:187]
	v_lshl_add_u64 v[116:117], s[46:47], 0, v[112:113]
	global_load_dwordx4 v[112:115], v[116:117], off
	s_nop 0
	global_load_dwordx4 v[116:119], v[116:117], off offset:16
	s_waitcnt vmcnt(1)
	v_mov_b32_e32 v120, v113
	v_mov_b32_e32 v121, v114
	v_mov_b32_e32 v113, v115
	v_pk_add_f32 v[112:113], v[120:121], v[112:113]
	s_waitcnt vmcnt(0)
; __device__ __forceinline__ unsigned pk2(float lo, float hi) { f32x2_t v = {lo, hi}; bf16x2_t b = __builtin_convertvector(v, bf16x2_t); return __builtin_bit_cast(unsigned, b); }
; __device__ __forceinline__ float dpp_ror1(float x) { return __int_as_float(__builtin_amdgcn_update_dpp(0, __float_as_int(x), 0x121, 0xf, 0xf, false)); }
; __device__ __forceinline__ float dpp_ror2(float x) { return __int_as_float(__builtin_amdgcn_update_dpp(0, __float_as_int(x), 0x122, 0xf, 0xf, false)); }
;     __device__ __forceinline__ float rsq(int row) const { const f32x4 q0 = *(const f32x4*)(pssq + (size_t)row * 8), q1 = *(const f32x4*)(pssq + (size_t)row * 8 + 4);
;         return rsqrtf(((q0.x + q0.y) + (q0.z + q0.w) + (q1.x + q1.y) + (q1.z + q1.w)) * (1.f / D) + EPS); }
;     __device__ __forceinline__ void operator()(const f32x4 (&acc)[2][2][4][2], const Unit& u, int wr, int wc, int fr, int fq) const {
;     ...
;             for (int m = 0; m < 4; ++m) { const int row = rowb + ai * HALF + m * 16; const float rs = rsq(row);
;                 f32x4 g[2], a[2];
; #pragma unroll
;                 for (int n = 0; n < 2; ++n) { g[n] = acc[ai][0][m][n] * rs; const f32x4 up = acc[ai][1][m][n] * rs;
; #pragma unroll
;                     for (int e = 0; e < 4; ++e) { const float r1c = dpp_ror1(g[n][e]), r1p = dpp_ror1(gprev[n][e]), r2c = dpp_ror2(g[n][e]), r2p = dpp_ror2(gprev[n][e]);
;                         const float p1 = fr >= 1 ? r1c : r1p, p2 = fr >= 2 ? r2c : r2p;
;                         const float c = bb[n][e] + w0[n][e] * p2 + w1[n][e] * p1 + w2[n][e] * g[n][e]; a[n][e] = c / (1.f + __expf(-c)) * up[e]; }
;                     if (ai == 0 && m == 0 && wr == 0 && fr < 2) { *(f32x4*)(firstg + ((size_t)u.pm * 2 + fr) * FF + ch0 + 4 * n) = g[n]; *(f32x4*)(firstup + ((size_t)u.pm * 2 + fr) * FF + ch0 + 4 * n) = up; }
;                     if (ai == 1 && m == 3 && wr == 1 && fr >= 14) *(f32x4*)(lastg + ((size_t)u.pm * 2 + (fr - 14)) * FF + ch0 + 4 * n) = g[n]; }
;                 if (!(ai == 0 && m == 0 && wr == 0 && fr < 2)) { u32x4 w; w.x = pk2(a[0][0], a[0][1]); w.y = pk2(a[0][2], a[0][3]); w.z = pk2(a[1][0], a[1][1]); w.w = pk2(a[1][2], a[1][3]);
;                     *(u32x4*)(ACT + (size_t)row * FF + ch0) = w; }
	v_mov_b32_e32 v114, v118
	v_mov_b32_e32 v115, v116
	v_mov_b32_e32 v116, v119
	v_pk_add_f32 v[114:115], v[114:115], v[116:117]
	v_add_f32_e32 v112, v112, v113
	v_add_f32_e32 v112, v112, v115
	v_add_f32_e32 v112, v114, v112
	v_fmamk_f32 v112, v112, 0x3a000000, v178
	s_nop 1
	v_rsq_f32_e32 v112, v112
	s_nop 0
	v_pk_mul_f32 v[108:109], v[108:109], v[112:113] op_sel_hi:[1,0]
	s_nop 0
	s_nop 0
	v_mov_b32_dpp v116, v108 row_ror:2 row_mask:0xf bank_mask:0xf
	v_mov_b32_dpp v117, v109 row_ror:2 row_mask:0xf bank_mask:0xf
	v_mov_b32_dpp v113, v108 row_ror:1 row_mask:0xf bank_mask:0xf
	v_mov_b32_dpp v114, v109 row_ror:1 row_mask:0xf bank_mask:0xf
	v_cndmask_b32_e64 v117, v144, v117, s[8:9]
	v_cndmask_b32_e64 v116, v142, v116, s[8:9]
	v_cndmask_b32_e64 v115, v114, v143, s[6:7]
	v_cndmask_b32_e64 v114, v113, v133, s[6:7]
	v_pk_fma_f32 v[116:117], v[44:45], v[116:117], v[52:53]
	s_nop 0
	v_pk_fma_f32 v[114:115], v[40:41], v[114:115], v[116:117]
	s_nop 0
	v_pk_fma_f32 v[108:109], v[48:49], v[108:109], v[114:115]
	s_nop 0
	v_mul_f32_e32 v113, 0xbfb8aa3b, v108
	v_exp_f32_e32 v114, v113
	v_mul_f32_e32 v113, 0xbfb8aa3b, v109
	v_exp_f32_e32 v115, v113
	s_nop 0
	v_pk_add_f32 v[114:115], v[114:115], 1.0 op_sel_hi:[1,0]
	s_nop 0
	v_rcp_f32_e32 v116, v115
	v_pk_mul_f32 v[110:111], v[110:111], v[112:113] op_sel_hi:[1,0]
	v_pk_mul_f32 v[106:107], v[106:107], v[112:113] op_sel_hi:[1,0]
	v_pk_mul_f32 v[104:105], v[104:105], v[112:113] op_sel_hi:[1,0]
	v_mul_f32_e32 v113, v109, v116
	v_mov_b32_dpp v118, v110 row_ror:2 row_mask:0xf bank_mask:0xf
	v_mov_b32_dpp v119, v111 row_ror:2 row_mask:0xf bank_mask:0xf
	v_mov_b32_dpp v116, v110 row_ror:1 row_mask:0xf bank_mask:0xf
	v_mov_b32_dpp v117, v111 row_ror:1 row_mask:0xf bank_mask:0xf
	v_cndmask_b32_e64 v119, v151, v119, s[8:9]
	v_cndmask_b32_e64 v118, v148, v118, s[8:9]
	v_cndmask_b32_e64 v117, v117, v149, s[6:7]
	v_cndmask_b32_e64 v116, v116, v147, s[6:7]
	v_pk_fma_f32 v[118:119], v[46:47], v[118:119], v[54:55]
	v_rcp_f32_e32 v121, v114
	v_pk_fma_f32 v[116:117], v[42:43], v[116:117], v[118:119]
	v_mov_b32_e32 v109, v113
	v_pk_fma_f32 v[110:111], v[50:51], v[110:111], v[116:117]
	v_mul_f32_e32 v116, 0xbfb8aa3b, v110
	v_mul_f32_e32 v117, 0xbfb8aa3b, v111
	v_exp_f32_e32 v116, v116
	v_exp_f32_e32 v117, v117
	s_nop 0
	v_pk_add_f32 v[116:117], v[116:117], 1.0 op_sel_hi:[1,0]
	v_rcp_f32_e32 v119, v117
	v_mul_f32_e32 v108, v108, v121
	v_pk_mul_f32 v[104:105], v[104:105], v[108:109]
	v_rcp_f32_e32 v120, v116
	v_mul_f32_e32 v109, v111, v119
	v_pk_mul_f32 v[100:101], v[100:101], v[112:113] op_sel_hi:[1,0]
	s_nop 1
	v_mov_b32_dpp v117, v100 row_ror:2 row_mask:0xf bank_mask:0xf
	s_nop 0
	v_mov_b32_dpp v118, v101 row_ror:2 row_mask:0xf bank_mask:0xf
	v_mov_b32_dpp v113, v100 row_ror:1 row_mask:0xf bank_mask:0xf
	v_mov_b32_dpp v114, v101 row_ror:1 row_mask:0xf bank_mask:0xf
	v_cndmask_b32_e64 v119, v185, v118, s[8:9]
	v_cndmask_b32_e64 v118, v146, v117, s[8:9]
	v_cndmask_b32_e64 v115, v114, v152, s[6:7]
	v_cndmask_b32_e64 v114, v113, v139, s[6:7]
	v_pk_fma_f32 v[118:119], v[72:73], v[118:119], v[76:77]
	v_pk_fma_f32 v[114:115], v[64:65], v[114:115], v[118:119]
	v_mul_f32_e32 v108, v110, v120
	v_pk_fma_f32 v[100:101], v[68:69], v[100:101], v[114:115]
	v_pk_mul_f32 v[106:107], v[106:107], v[108:109]
	v_mul_f32_e32 v113, 0xbfb8aa3b, v100
	v_exp_f32_e32 v114, v113
	v_mul_f32_e32 v113, 0xbfb8aa3b, v101
	v_exp_f32_e32 v115, v113
	v_pk_mul_f32 v[102:103], v[102:103], v[112:113] op_sel_hi:[1,0]
	v_pk_mul_f32 v[98:99], v[98:99], v[112:113] op_sel_hi:[1,0]
	v_pk_mul_f32 v[96:97], v[96:97], v[112:113] op_sel_hi:[1,0]
	v_pk_add_f32 v[108:109], v[114:115], 1.0 op_sel_hi:[1,0]
	s_nop 0
	v_rcp_f32_e32 v111, v109
	s_nop 0
	v_mul_f32_e32 v101, v101, v111
	v_mov_b32_dpp v112, v102 row_ror:2 row_mask:0xf bank_mask:0xf
	v_mov_b32_dpp v113, v103 row_ror:2 row_mask:0xf bank_mask:0xf
	v_mov_b32_dpp v110, v102 row_ror:1 row_mask:0xf bank_mask:0xf
	v_mov_b32_dpp v111, v103 row_ror:1 row_mask:0xf bank_mask:0xf
	v_cndmask_b32_e64 v113, v156, v113, s[8:9]
	v_cndmask_b32_e64 v112, v141, v112, s[8:9]
	v_cndmask_b32_e64 v111, v111, v145, s[6:7]
	v_cndmask_b32_e64 v110, v110, v140, s[6:7]
	v_pk_fma_f32 v[112:113], v[74:75], v[112:113], v[78:79]
	v_rcp_f32_e32 v115, v108
	v_pk_fma_f32 v[110:111], v[66:67], v[110:111], v[112:113]
	v_pk_fma_f32 v[102:103], v[70:71], v[102:103], v[110:111]
	v_mul_f32_e32 v110, 0xbfb8aa3b, v102
	v_mul_f32_e32 v111, 0xbfb8aa3b, v103
	v_exp_f32_e32 v110, v110
	v_exp_f32_e32 v111, v111
	s_nop 0
	v_pk_add_f32 v[110:111], v[110:111], 1.0 op_sel_hi:[1,0]
	v_rcp_f32_e32 v113, v111
	v_mul_f32_e32 v100, v100, v115
	v_pk_mul_f32 v[100:101], v[96:97], v[100:101]
	v_rcp_f32_e32 v109, v110
	v_mul_f32_e32 v97, v103, v113
	v_mul_f32_e32 v96, v102, v109
	v_pk_mul_f32 v[102:103], v[98:99], v[96:97]
	v_cvt_pk_bf16_f32 v98, v100, v101
	v_mad_i64_i32 v[100:101], s[16:17], v186, s33, v[128:129]
	v_cvt_pk_bf16_f32 v96, v104, v105
	v_cvt_pk_bf16_f32 v97, v106, v107
	v_cvt_pk_bf16_f32 v99, v102, v103
	v_lshl_add_u64 v[100:101], v[100:101], 0, v[130:131]
	global_store_dwordx4 v[100:101], v[96:99], off
	s_nop 1
	v_add_u32_e32 v96, 0x80, v184
	v_ashrrev_i32_e32 v97, 31, v96
	v_lshlrev_b64 v[98:99], 5, v[96:97]
	v_lshl_add_u64 v[102:103], s[46:47], 0, v[98:99]
	global_load_dwordx4 v[98:101], v[102:103], off
	s_nop 0
	global_load_dwordx4 v[102:105], v[102:103], off offset:16
	ds_read_b128 v[106:109], v204 offset:144
	ds_read_b128 v[110:113], v204 offset:16
	ds_read_b128 v[114:117], v204
	ds_read_b128 v[118:121], v204 offset:128
	s_waitcnt lgkmcnt(2)
	v_cndmask_b32_e64 v97, v113, v109, s[10:11]
	v_cndmask_b32_e64 v112, v112, v108, s[10:11]
	v_cndmask_b32_e64 v106, v110, v106, s[10:11]
	s_waitcnt vmcnt(1)
; __device__ __forceinline__ unsigned pk2(float lo, float hi) { f32x2_t v = {lo, hi}; bf16x2_t b = __builtin_convertvector(v, bf16x2_t); return __builtin_bit_cast(unsigned, b); }
; __device__ __forceinline__ float dpp_ror1(float x) { return __int_as_float(__builtin_amdgcn_update_dpp(0, __float_as_int(x), 0x121, 0xf, 0xf, false)); }
; __device__ __forceinline__ float dpp_ror2(float x) { return __int_as_float(__builtin_amdgcn_update_dpp(0, __float_as_int(x), 0x122, 0xf, 0xf, false)); }
;     __device__ __forceinline__ float rsq(int row) const { const f32x4 q0 = *(const f32x4*)(pssq + (size_t)row * 8), q1 = *(const f32x4*)(pssq + (size_t)row * 8 + 4);
;         return rsqrtf(((q0.x + q0.y) + (q0.z + q0.w) + (q1.x + q1.y) + (q1.z + q1.w)) * (1.f / D) + EPS); }
;     __device__ __forceinline__ void operator()(const f32x4 (&acc)[2][2][4][2], const Unit& u, int wr, int wc, int fr, int fq) const {
;     ...
;             for (int m = 0; m < 4; ++m) { const int row = rowb + ai * HALF + m * 16; const float rs = rsq(row);
;                 f32x4 g[2], a[2];
; #pragma unroll
;                 for (int n = 0; n < 2; ++n) { g[n] = acc[ai][0][m][n] * rs; const f32x4 up = acc[ai][1][m][n] * rs;
; #pragma unroll
;                     for (int e = 0; e < 4; ++e) { const float r1c = dpp_ror1(g[n][e]), r1p = dpp_ror1(gprev[n][e]), r2c = dpp_ror2(g[n][e]), r2p = dpp_ror2(gprev[n][e]);
;                         const float p1 = fr >= 1 ? r1c : r1p, p2 = fr >= 2 ? r2c : r2p;
;                         const float c = bb[n][e] + w0[n][e] * p2 + w1[n][e] * p1 + w2[n][e] * g[n][e]; a[n][e] = c / (1.f + __expf(-c)) * up[e]; }
;                     if (ai == 0 && m == 0 && wr == 0 && fr < 2) { *(f32x4*)(firstg + ((size_t)u.pm * 2 + fr) * FF + ch0 + 4 * n) = g[n]; *(f32x4*)(firstup + ((size_t)u.pm * 2 + fr) * FF + ch0 + 4 * n) = up; }
;                     if (ai == 1 && m == 3 && wr == 1 && fr >= 14) *(f32x4*)(lastg + ((size_t)u.pm * 2 + (fr - 14)) * FF + ch0 + 4 * n) = g[n]; }
;                 if (!(ai == 0 && m == 0 && wr == 0 && fr < 2)) { u32x4 w; w.x = pk2(a[0][0], a[0][1]); w.y = pk2(a[0][2], a[0][3]); w.z = pk2(a[1][0], a[1][1]); w.w = pk2(a[1][2], a[1][3]);
;                     *(u32x4*)(ACT + (size_t)row * FF + ch0) = w; }
	v_mov_b32_e32 v108, v99
	v_mov_b32_e32 v109, v100
	v_mov_b32_e32 v99, v101
	v_pk_add_f32 v[98:99], v[108:109], v[98:99]
	s_waitcnt vmcnt(0)
	v_mov_b32_e32 v100, v104
	v_mov_b32_e32 v101, v102
	v_mov_b32_e32 v102, v105
	v_pk_add_f32 v[100:101], v[100:101], v[102:103]
	v_add_f32_e32 v98, v98, v99
	v_add_f32_e32 v98, v98, v101
	v_add_f32_e32 v98, v100, v98
	v_fmamk_f32 v98, v98, 0x3a000000, v178
	s_waitcnt lgkmcnt(0)
	v_cndmask_b32_e64 v100, v115, v119, s[10:11]
	v_cndmask_b32_e64 v101, v114, v118, s[10:11]
	v_rsq_f32_e32 v98, v98
	v_cndmask_b32_e64 v99, v111, v107, s[10:11]
	v_pk_mul_f32 v[92:93], v[92:93], v[98:99] op_sel_hi:[1,0]
	s_nop 1
	v_mov_b32_dpp v107, v92 row_ror:1 row_mask:0xf bank_mask:0xf
	v_mov_b32_dpp v102, v101 row_ror:1 row_mask:0xf bank_mask:0xf
	v_mov_b32_dpp v108, v92 row_ror:2 row_mask:0xf bank_mask:0xf
	v_mov_b32_dpp v104, v101 row_ror:2 row_mask:0xf bank_mask:0xf
	v_mov_b32_dpp v111, v93 row_ror:2 row_mask:0xf bank_mask:0xf
	v_mov_b32_dpp v103, v100 row_ror:2 row_mask:0xf bank_mask:0xf
	v_mov_b32_dpp v109, v93 row_ror:1 row_mask:0xf bank_mask:0xf
	v_mov_b32_dpp v101, v100 row_ror:1 row_mask:0xf bank_mask:0xf
	v_cndmask_b32_e64 v100, v107, v102, s[6:7]
	v_cndmask_b32_e64 v103, v103, v111, s[8:9]
	v_cndmask_b32_e64 v102, v104, v108, s[8:9]
	v_cndmask_b32_e64 v101, v109, v101, s[6:7]
	v_pk_fma_f32 v[102:103], v[44:45], v[102:103], v[52:53]
	v_pk_mul_f32 v[94:95], v[94:95], v[98:99] op_sel_hi:[1,0]
	v_pk_fma_f32 v[100:101], v[40:41], v[100:101], v[102:103]
	v_cndmask_b32_e64 v102, v117, v121, s[10:11]
	v_pk_fma_f32 v[92:93], v[48:49], v[92:93], v[100:101]
	v_cndmask_b32_e64 v103, v116, v120, s[10:11]
	v_mul_f32_e32 v100, 0xbfb8aa3b, v92
	v_mul_f32_e32 v101, 0xbfb8aa3b, v93
	v_exp_f32_e32 v100, v100
	v_exp_f32_e32 v101, v101
	s_nop 0
	v_pk_add_f32 v[100:101], v[100:101], 1.0 op_sel_hi:[1,0]
	v_rcp_f32_e32 v105, v101
	v_mov_b32_dpp v115, v94 row_ror:1 row_mask:0xf bank_mask:0xf
	v_mov_b32_dpp v116, v94 row_ror:2 row_mask:0xf bank_mask:0xf
	v_mov_b32_dpp v117, v103 row_ror:2 row_mask:0xf bank_mask:0xf
	v_mul_f32_e32 v93, v93, v105
	v_mov_b32_dpp v104, v103 row_ror:1 row_mask:0xf bank_mask:0xf
	v_mov_b32_dpp v119, v95 row_ror:2 row_mask:0xf bank_mask:0xf
	v_mov_b32_dpp v105, v102 row_ror:2 row_mask:0xf bank_mask:0xf
	v_mov_b32_dpp v118, v95 row_ror:1 row_mask:0xf bank_mask:0xf
	v_mov_b32_dpp v103, v102 row_ror:1 row_mask:0xf bank_mask:0xf
	v_cndmask_b32_e64 v102, v115, v104, s[6:7]
	v_cndmask_b32_e64 v105, v105, v119, s[8:9]
	v_cndmask_b32_e64 v104, v117, v116, s[8:9]
	v_cndmask_b32_e64 v103, v118, v103, s[6:7]
	v_pk_fma_f32 v[104:105], v[46:47], v[104:105], v[54:55]
	v_rcp_f32_e32 v114, v100
	v_pk_fma_f32 v[102:103], v[42:43], v[102:103], v[104:105]
	v_pk_mul_f32 v[88:89], v[88:89], v[98:99] op_sel_hi:[1,0]
	v_pk_fma_f32 v[94:95], v[50:51], v[94:95], v[102:103]
	v_mul_f32_e32 v102, 0xbfb8aa3b, v94
	v_mul_f32_e32 v103, 0xbfb8aa3b, v95
	v_exp_f32_e32 v102, v102
	v_exp_f32_e32 v103, v103
	s_nop 0
	v_pk_add_f32 v[102:103], v[102:103], 1.0 op_sel_hi:[1,0]
	v_rcp_f32_e32 v105, v103
	v_mul_f32_e32 v92, v92, v114
	v_pk_mul_f32 v[88:89], v[88:89], v[92:93]
	v_rcp_f32_e32 v110, v102
	v_mul_f32_e32 v93, v95, v105
	v_pk_mul_f32 v[84:85], v[84:85], v[98:99] op_sel_hi:[1,0]
	v_mov_b32_dpp v100, v106 row_ror:1 row_mask:0xf bank_mask:0xf
	s_nop 0
	v_mov_b32_dpp v113, v84 row_ror:2 row_mask:0xf bank_mask:0xf
	v_mov_b32_dpp v104, v106 row_ror:2 row_mask:0xf bank_mask:0xf
	v_mov_b32_dpp v114, v85 row_ror:2 row_mask:0xf bank_mask:0xf
	v_mov_b32_dpp v105, v99 row_ror:2 row_mask:0xf bank_mask:0xf
	v_mov_b32_dpp v103, v84 row_ror:1 row_mask:0xf bank_mask:0xf
	v_mov_b32_dpp v106, v85 row_ror:1 row_mask:0xf bank_mask:0xf
	v_mov_b32_dpp v101, v99 row_ror:1 row_mask:0xf bank_mask:0xf
	v_cndmask_b32_e64 v105, v105, v114, s[8:9]
	v_cndmask_b32_e64 v104, v104, v113, s[8:9]
	v_cndmask_b32_e64 v101, v106, v101, s[6:7]
	v_cndmask_b32_e64 v100, v103, v100, s[6:7]
	v_pk_fma_f32 v[104:105], v[72:73], v[104:105], v[76:77]
	v_pk_mul_f32 v[90:91], v[90:91], v[98:99] op_sel_hi:[1,0]
	v_pk_fma_f32 v[100:101], v[64:65], v[100:101], v[104:105]
	v_pk_fma_f32 v[84:85], v[68:69], v[84:85], v[100:101]
	v_mul_f32_e32 v92, v94, v110
	v_mul_f32_e32 v99, 0xbfb8aa3b, v84
	v_exp_f32_e32 v100, v99
	v_mul_f32_e32 v99, 0xbfb8aa3b, v85
	v_exp_f32_e32 v101, v99
	v_pk_mul_f32 v[90:91], v[90:91], v[92:93]
	v_pk_mul_f32 v[86:87], v[86:87], v[98:99] op_sel_hi:[1,0]
	v_pk_mul_f32 v[82:83], v[82:83], v[98:99] op_sel_hi:[1,0]
	v_pk_add_f32 v[92:93], v[100:101], 1.0 op_sel_hi:[1,0]
	v_pk_mul_f32 v[80:81], v[80:81], v[98:99] op_sel_hi:[1,0]
	v_rcp_f32_e32 v95, v93
	s_nop 0
	v_mul_f32_e32 v85, v85, v95
	v_mov_b32_dpp v94, v112 row_ror:1 row_mask:0xf bank_mask:0xf
	v_mov_b32_dpp v98, v112 row_ror:2 row_mask:0xf bank_mask:0xf
	v_mov_b32_dpp v105, v86 row_ror:2 row_mask:0xf bank_mask:0xf
	v_mov_b32_dpp v112, v87 row_ror:2 row_mask:0xf bank_mask:0xf
	v_mov_b32_dpp v99, v97 row_ror:2 row_mask:0xf bank_mask:0xf
	v_mov_b32_dpp v104, v86 row_ror:1 row_mask:0xf bank_mask:0xf
	v_mov_b32_dpp v110, v87 row_ror:1 row_mask:0xf bank_mask:0xf
	v_mov_b32_dpp v95, v97 row_ror:1 row_mask:0xf bank_mask:0xf
	v_cndmask_b32_e64 v99, v99, v112, s[8:9]
	v_cndmask_b32_e64 v98, v98, v105, s[8:9]
	v_cndmask_b32_e64 v95, v110, v95, s[6:7]
	v_cndmask_b32_e64 v94, v104, v94, s[6:7]
	v_pk_fma_f32 v[98:99], v[74:75], v[98:99], v[78:79]
	v_rcp_f32_e32 v101, v92
	v_pk_fma_f32 v[94:95], v[66:67], v[94:95], v[98:99]
	v_pk_fma_f32 v[86:87], v[70:71], v[86:87], v[94:95]
	v_mul_f32_e32 v94, 0xbfb8aa3b, v86
	v_mul_f32_e32 v95, 0xbfb8aa3b, v87
	v_exp_f32_e32 v94, v94
	v_exp_f32_e32 v95, v95
	s_nop 0
	v_pk_add_f32 v[94:95], v[94:95], 1.0 op_sel_hi:[1,0]
	v_rcp_f32_e32 v98, v95
	v_mul_f32_e32 v84, v84, v101
	v_pk_mul_f32 v[84:85], v[80:81], v[84:85]
	v_rcp_f32_e32 v93, v94
	v_mul_f32_e32 v81, v87, v98
	v_mul_f32_e32 v80, v86, v93
	v_pk_mul_f32 v[86:87], v[82:83], v[80:81]
	v_cvt_pk_bf16_f32 v82, v84, v85
	v_mad_i64_i32 v[84:85], s[16:17], v96, s33, v[128:129]
	v_cvt_pk_bf16_f32 v80, v88, v89
	v_cvt_pk_bf16_f32 v81, v90, v91
	v_cvt_pk_bf16_f32 v83, v86, v87
	v_lshl_add_u64 v[84:85], v[84:85], 0, v[130:131]
	global_store_dwordx4 v[84:85], v[80:83], off
	s_nop 1
	v_add_u32_e32 v80, 0x90, v184
	s_nop 0
	v_ashrrev_i32_e32 v81, 31, v80
	v_lshlrev_b64 v[82:83], 5, v[80:81]
	v_lshl_add_u64 v[86:87], s[46:47], 0, v[82:83]
	global_load_dwordx4 v[82:85], v[86:87], off
	s_nop 0
	global_load_dwordx4 v[86:89], v[86:87], off offset:16
	s_waitcnt vmcnt(1)
; __device__ __forceinline__ unsigned pk2(float lo, float hi) { f32x2_t v = {lo, hi}; bf16x2_t b = __builtin_convertvector(v, bf16x2_t); return __builtin_bit_cast(unsigned, b); }
; __device__ __forceinline__ float dpp_ror1(float x) { return __int_as_float(__builtin_amdgcn_update_dpp(0, __float_as_int(x), 0x121, 0xf, 0xf, false)); }
; __device__ __forceinline__ float dpp_ror2(float x) { return __int_as_float(__builtin_amdgcn_update_dpp(0, __float_as_int(x), 0x122, 0xf, 0xf, false)); }
;     __device__ __forceinline__ float rsq(int row) const { const f32x4 q0 = *(const f32x4*)(pssq + (size_t)row * 8), q1 = *(const f32x4*)(pssq + (size_t)row * 8 + 4);
;         return rsqrtf(((q0.x + q0.y) + (q0.z + q0.w) + (q1.x + q1.y) + (q1.z + q1.w)) * (1.f / D) + EPS); }
;     __device__ __forceinline__ void operator()(const f32x4 (&acc)[2][2][4][2], const Unit& u, int wr, int wc, int fr, int fq) const {
;     ...
;             for (int m = 0; m < 4; ++m) { const int row = rowb + ai * HALF + m * 16; const float rs = rsq(row);
;                 f32x4 g[2], a[2];
; #pragma unroll
;                 for (int n = 0; n < 2; ++n) { g[n] = acc[ai][0][m][n] * rs; const f32x4 up = acc[ai][1][m][n] * rs;
; #pragma unroll
;                     for (int e = 0; e < 4; ++e) { const float r1c = dpp_ror1(g[n][e]), r1p = dpp_ror1(gprev[n][e]), r2c = dpp_ror2(g[n][e]), r2p = dpp_ror2(gprev[n][e]);
;                         const float p1 = fr >= 1 ? r1c : r1p, p2 = fr >= 2 ? r2c : r2p;
;                         const float c = bb[n][e] + w0[n][e] * p2 + w1[n][e] * p1 + w2[n][e] * g[n][e]; a[n][e] = c / (1.f + __expf(-c)) * up[e]; }
;                     if (ai == 0 && m == 0 && wr == 0 && fr < 2) { *(f32x4*)(firstg + ((size_t)u.pm * 2 + fr) * FF + ch0 + 4 * n) = g[n]; *(f32x4*)(firstup + ((size_t)u.pm * 2 + fr) * FF + ch0 + 4 * n) = up; }
;                     if (ai == 1 && m == 3 && wr == 1 && fr >= 14) *(f32x4*)(lastg + ((size_t)u.pm * 2 + (fr - 14)) * FF + ch0 + 4 * n) = g[n]; }
;                 if (!(ai == 0 && m == 0 && wr == 0 && fr < 2)) { u32x4 w; w.x = pk2(a[0][0], a[0][1]); w.y = pk2(a[0][2], a[0][3]); w.z = pk2(a[1][0], a[1][1]); w.w = pk2(a[1][2], a[1][3]);
;                     *(u32x4*)(ACT + (size_t)row * FF + ch0) = w; }
	v_mov_b32_e32 v90, v83
	v_mov_b32_e32 v91, v84
	v_mov_b32_e32 v83, v85
	v_pk_add_f32 v[82:83], v[90:91], v[82:83]
	s_waitcnt vmcnt(0)
	v_mov_b32_e32 v84, v88
	v_mov_b32_e32 v85, v86
	v_mov_b32_e32 v86, v89
	v_pk_add_f32 v[84:85], v[84:85], v[86:87]
	v_add_f32_e32 v81, v82, v83
	v_add_f32_e32 v81, v81, v85
	v_add_f32_e32 v81, v84, v81
	v_fmamk_f32 v81, v81, 0x3a000000, v178
	s_nop 1
	v_rsq_f32_e32 v82, v81
	s_nop 0
	v_pk_mul_f32 v[60:61], v[60:61], v[82:83] op_sel_hi:[1,0]
	s_nop 0
	s_nop 0
	v_mov_b32_dpp v90, v60 row_ror:2 row_mask:0xf bank_mask:0xf
	v_mov_b32_dpp v92, v61 row_ror:2 row_mask:0xf bank_mask:0xf
	v_mov_b32_dpp v81, v60 row_ror:1 row_mask:0xf bank_mask:0xf
	v_mov_b32_dpp v91, v61 row_ror:1 row_mask:0xf bank_mask:0xf
	v_cndmask_b32_e64 v87, v111, v92, s[8:9]
	v_cndmask_b32_e64 v86, v108, v90, s[8:9]
	v_cndmask_b32_e64 v85, v91, v109, s[6:7]
	v_cndmask_b32_e64 v84, v81, v107, s[6:7]
	v_pk_fma_f32 v[86:87], v[44:45], v[86:87], v[52:53]
	s_nop 0
	v_pk_fma_f32 v[84:85], v[40:41], v[84:85], v[86:87]
	s_nop 0
	v_pk_fma_f32 v[60:61], v[48:49], v[60:61], v[84:85]
	s_nop 0
	v_mul_f32_e32 v83, 0xbfb8aa3b, v60
	v_exp_f32_e32 v84, v83
	v_mul_f32_e32 v83, 0xbfb8aa3b, v61
	v_exp_f32_e32 v85, v83
	s_nop 0
	v_pk_add_f32 v[84:85], v[84:85], 1.0 op_sel_hi:[1,0]
	s_nop 0
	v_rcp_f32_e32 v86, v85
	v_pk_mul_f32 v[62:63], v[62:63], v[82:83] op_sel_hi:[1,0]
	v_pk_mul_f32 v[58:59], v[58:59], v[82:83] op_sel_hi:[1,0]
	v_pk_mul_f32 v[56:57], v[56:57], v[82:83] op_sel_hi:[1,0]
	v_mov_b32_dpp v96, v62 row_ror:2 row_mask:0xf bank_mask:0xf
	v_mov_b32_dpp v98, v63 row_ror:2 row_mask:0xf bank_mask:0xf
	v_mul_f32_e32 v83, v61, v86
	v_mov_b32_dpp v95, v62 row_ror:1 row_mask:0xf bank_mask:0xf
	v_mov_b32_dpp v97, v63 row_ror:1 row_mask:0xf bank_mask:0xf
	v_cndmask_b32_e64 v89, v119, v98, s[8:9]
	v_cndmask_b32_e64 v88, v116, v96, s[8:9]
	v_cndmask_b32_e64 v87, v97, v118, s[6:7]
	v_cndmask_b32_e64 v86, v95, v115, s[6:7]
	v_pk_fma_f32 v[88:89], v[46:47], v[88:89], v[54:55]
	v_rcp_f32_e32 v94, v84
	v_pk_fma_f32 v[86:87], v[42:43], v[86:87], v[88:89]
	v_mov_b32_e32 v61, v83
	v_pk_fma_f32 v[62:63], v[50:51], v[62:63], v[86:87]
	v_mul_f32_e32 v86, 0xbfb8aa3b, v62
	v_mul_f32_e32 v87, 0xbfb8aa3b, v63
	v_exp_f32_e32 v86, v86
	v_exp_f32_e32 v87, v87
	s_nop 0
	v_pk_add_f32 v[86:87], v[86:87], 1.0 op_sel_hi:[1,0]
	v_rcp_f32_e32 v89, v87
	v_mul_f32_e32 v60, v60, v94
	v_pk_mul_f32 v[56:57], v[56:57], v[60:61]
	v_rcp_f32_e32 v93, v86
	v_mul_f32_e32 v61, v63, v89
	v_pk_mul_f32 v[36:37], v[36:37], v[82:83] op_sel_hi:[1,0]
	s_nop 0
	s_nop 0
	v_mov_b32_dpp v94, v36 row_ror:2 row_mask:0xf bank_mask:0xf
	v_mov_b32_dpp v100, v37 row_ror:2 row_mask:0xf bank_mask:0xf
	v_mov_b32_dpp v87, v36 row_ror:1 row_mask:0xf bank_mask:0xf
	v_mov_b32_dpp v99, v37 row_ror:1 row_mask:0xf bank_mask:0xf
	v_cndmask_b32_e64 v89, v114, v100, s[8:9]
	v_cndmask_b32_e64 v88, v113, v94, s[8:9]
	v_cndmask_b32_e64 v85, v99, v106, s[6:7]
	v_cndmask_b32_e64 v84, v87, v103, s[6:7]
	v_pk_fma_f32 v[88:89], v[72:73], v[88:89], v[76:77]
	v_pk_fma_f32 v[84:85], v[64:65], v[84:85], v[88:89]
	v_pk_fma_f32 v[36:37], v[68:69], v[36:37], v[84:85]
	v_mul_f32_e32 v60, v62, v93
	v_mul_f32_e32 v83, 0xbfb8aa3b, v36
	v_exp_f32_e32 v84, v83
	v_mul_f32_e32 v83, 0xbfb8aa3b, v37
	v_exp_f32_e32 v85, v83
	v_pk_mul_f32 v[58:59], v[58:59], v[60:61]
	v_pk_mul_f32 v[38:39], v[38:39], v[82:83] op_sel_hi:[1,0]
	v_pk_mul_f32 v[34:35], v[34:35], v[82:83] op_sel_hi:[1,0]
	v_pk_add_f32 v[60:61], v[84:85], 1.0 op_sel_hi:[1,0]
	v_pk_mul_f32 v[32:33], v[32:33], v[82:83] op_sel_hi:[1,0]
	v_rcp_f32_e32 v63, v61
	v_mov_b32_dpp v89, v38 row_ror:2 row_mask:0xf bank_mask:0xf
	v_mov_b32_dpp v101, v39 row_ror:2 row_mask:0xf bank_mask:0xf
	v_mov_b32_dpp v88, v38 row_ror:1 row_mask:0xf bank_mask:0xf
	v_mov_b32_dpp v93, v39 row_ror:1 row_mask:0xf bank_mask:0xf
	v_cndmask_b32_e64 v83, v112, v101, s[8:9]
	v_cndmask_b32_e64 v82, v105, v89, s[8:9]
	v_mul_f32_e32 v37, v37, v63
	v_cndmask_b32_e64 v63, v93, v110, s[6:7]
	v_cndmask_b32_e64 v62, v88, v104, s[6:7]
	v_pk_fma_f32 v[82:83], v[74:75], v[82:83], v[78:79]
	v_rcp_f32_e32 v85, v60
	v_pk_fma_f32 v[62:63], v[66:67], v[62:63], v[82:83]
	v_pk_fma_f32 v[38:39], v[70:71], v[38:39], v[62:63]
	v_mul_f32_e32 v62, 0xbfb8aa3b, v38
	v_mul_f32_e32 v63, 0xbfb8aa3b, v39
	v_exp_f32_e32 v62, v62
	v_exp_f32_e32 v63, v63
	s_nop 0
	v_pk_add_f32 v[62:63], v[62:63], 1.0 op_sel_hi:[1,0]
	v_rcp_f32_e32 v83, v63
	v_mul_f32_e32 v36, v36, v85
	v_pk_mul_f32 v[36:37], v[32:33], v[36:37]
	v_rcp_f32_e32 v61, v62
	v_mul_f32_e32 v33, v39, v83
	v_mul_f32_e32 v32, v38, v61
	v_pk_mul_f32 v[38:39], v[34:35], v[32:33]
	v_cvt_pk_bf16_f32 v34, v36, v37
	v_mad_i64_i32 v[36:37], s[16:17], v80, s33, v[128:129]
	v_cvt_pk_bf16_f32 v32, v56, v57
	v_cvt_pk_bf16_f32 v33, v58, v59
	v_cvt_pk_bf16_f32 v35, v38, v39
	v_lshl_add_u64 v[36:37], v[36:37], 0, v[130:131]
	global_store_dwordx4 v[36:37], v[32:35], off
	s_nop 1
	v_add_u32_e32 v32, 0xa0, v184
	v_ashrrev_i32_e32 v33, 31, v32
	v_lshlrev_b64 v[34:35], 5, v[32:33]
	v_lshl_add_u64 v[38:39], s[46:47], 0, v[34:35]
	global_load_dwordx4 v[34:37], v[38:39], off
	global_load_dwordx4 v[56:59], v[38:39], off offset:16
	s_waitcnt vmcnt(1)
	v_mov_b32_e32 v38, v35
	v_mov_b32_e32 v39, v36
	v_mov_b32_e32 v35, v37
	v_pk_add_f32 v[34:35], v[38:39], v[34:35]
	s_waitcnt vmcnt(0)
; __device__ __forceinline__ unsigned pk2(float lo, float hi) { f32x2_t v = {lo, hi}; bf16x2_t b = __builtin_convertvector(v, bf16x2_t); return __builtin_bit_cast(unsigned, b); }
; __device__ __forceinline__ float dpp_ror1(float x) { return __int_as_float(__builtin_amdgcn_update_dpp(0, __float_as_int(x), 0x121, 0xf, 0xf, false)); }
; __device__ __forceinline__ float dpp_ror2(float x) { return __int_as_float(__builtin_amdgcn_update_dpp(0, __float_as_int(x), 0x122, 0xf, 0xf, false)); }
;     __device__ __forceinline__ float rsq(int row) const { const f32x4 q0 = *(const f32x4*)(pssq + (size_t)row * 8), q1 = *(const f32x4*)(pssq + (size_t)row * 8 + 4);
;         return rsqrtf(((q0.x + q0.y) + (q0.z + q0.w) + (q1.x + q1.y) + (q1.z + q1.w)) * (1.f / D) + EPS); }
;     __device__ __forceinline__ void operator()(const f32x4 (&acc)[2][2][4][2], const Unit& u, int wr, int wc, int fr, int fq) const {
;     ...
;             for (int m = 0; m < 4; ++m) { const int row = rowb + ai * HALF + m * 16; const float rs = rsq(row);
;                 f32x4 g[2], a[2];
; #pragma unroll
;                 for (int n = 0; n < 2; ++n) { g[n] = acc[ai][0][m][n] * rs; const f32x4 up = acc[ai][1][m][n] * rs;
; #pragma unroll
;                     for (int e = 0; e < 4; ++e) { const float r1c = dpp_ror1(g[n][e]), r1p = dpp_ror1(gprev[n][e]), r2c = dpp_ror2(g[n][e]), r2p = dpp_ror2(gprev[n][e]);
;                         const float p1 = fr >= 1 ? r1c : r1p, p2 = fr >= 2 ? r2c : r2p;
;                         const float c = bb[n][e] + w0[n][e] * p2 + w1[n][e] * p1 + w2[n][e] * g[n][e]; a[n][e] = c / (1.f + __expf(-c)) * up[e]; }
;                     if (ai == 0 && m == 0 && wr == 0 && fr < 2) { *(f32x4*)(firstg + ((size_t)u.pm * 2 + fr) * FF + ch0 + 4 * n) = g[n]; *(f32x4*)(firstup + ((size_t)u.pm * 2 + fr) * FF + ch0 + 4 * n) = up; }
;                     if (ai == 1 && m == 3 && wr == 1 && fr >= 14) *(f32x4*)(lastg + ((size_t)u.pm * 2 + (fr - 14)) * FF + ch0 + 4 * n) = g[n]; }
;                 if (!(ai == 0 && m == 0 && wr == 0 && fr < 2)) { u32x4 w; w.x = pk2(a[0][0], a[0][1]); w.y = pk2(a[0][2], a[0][3]); w.z = pk2(a[1][0], a[1][1]); w.w = pk2(a[1][2], a[1][3]);
;                     *(u32x4*)(ACT + (size_t)row * FF + ch0) = w; }
	v_mov_b32_e32 v36, v58
	v_mov_b32_e32 v37, v56
	v_mov_b32_e32 v56, v59
	v_pk_add_f32 v[36:37], v[36:37], v[56:57]
	v_add_f32_e32 v33, v34, v35
	v_add_f32_e32 v33, v33, v37
	v_add_f32_e32 v33, v36, v33
	v_fmamk_f32 v33, v33, 0x3a000000, v178
	s_nop 1
	v_rsq_f32_e32 v36, v33
	s_nop 0
	v_pk_mul_f32 v[38:39], v[28:29], v[36:37] op_sel_hi:[1,0]
	s_nop 1
	v_mov_b32_dpp v29, v38 row_ror:2 row_mask:0xf bank_mask:0xf
	s_nop 0
	v_mov_b32_dpp v34, v39 row_ror:2 row_mask:0xf bank_mask:0xf
	v_mov_b32_dpp v28, v38 row_ror:1 row_mask:0xf bank_mask:0xf
	v_mov_b32_dpp v33, v39 row_ror:1 row_mask:0xf bank_mask:0xf
	v_cndmask_b32_e64 v59, v92, v34, s[8:9]
	v_cndmask_b32_e64 v58, v90, v29, s[8:9]
	v_cndmask_b32_e64 v57, v33, v91, s[6:7]
	v_cndmask_b32_e64 v56, v28, v81, s[6:7]
	v_pk_fma_f32 v[58:59], v[44:45], v[58:59], v[52:53]
	s_nop 0
	v_pk_fma_f32 v[56:57], v[40:41], v[56:57], v[58:59]
	s_nop 0
	v_pk_fma_f32 v[38:39], v[48:49], v[38:39], v[56:57]
	s_nop 0
	v_mul_f32_e32 v35, 0xbfb8aa3b, v38
	v_exp_f32_e32 v56, v35
	v_mul_f32_e32 v35, 0xbfb8aa3b, v39
	v_exp_f32_e32 v57, v35
	s_nop 0
	v_pk_add_f32 v[56:57], v[56:57], 1.0 op_sel_hi:[1,0]
	s_nop 0
	v_rcp_f32_e32 v37, v57
	s_nop 0
	v_pk_mul_f32 v[60:61], v[26:27], v[36:37] op_sel_hi:[1,0]
	v_pk_mul_f32 v[58:59], v[30:31], v[36:37] op_sel_hi:[1,0]
	v_pk_mul_f32 v[24:25], v[24:25], v[36:37] op_sel_hi:[1,0]
	v_rcp_f32_e32 v82, v56
	v_mul_f32_e32 v39, v39, v37
	v_mov_b32_dpp v27, v58 row_ror:2 row_mask:0xf bank_mask:0xf
	v_mov_b32_dpp v31, v59 row_ror:2 row_mask:0xf bank_mask:0xf
	v_mov_b32_dpp v26, v58 row_ror:1 row_mask:0xf bank_mask:0xf
	v_mov_b32_dpp v30, v59 row_ror:1 row_mask:0xf bank_mask:0xf
	v_cndmask_b32_e64 v81, v98, v31, s[8:9]
	v_cndmask_b32_e64 v80, v96, v27, s[8:9]
	v_cndmask_b32_e64 v63, v30, v97, s[6:7]
	v_cndmask_b32_e64 v62, v26, v95, s[6:7]
	v_pk_fma_f32 v[80:81], v[46:47], v[80:81], v[54:55]
	v_pk_fma_f32 v[62:63], v[42:43], v[62:63], v[80:81]
	v_pk_fma_f32 v[58:59], v[50:51], v[58:59], v[62:63]
	v_mul_f32_e32 v62, 0xbfb8aa3b, v58
	v_mul_f32_e32 v63, 0xbfb8aa3b, v59
	v_exp_f32_e32 v62, v62
	v_exp_f32_e32 v63, v63
	s_nop 0
	v_pk_add_f32 v[62:63], v[62:63], 1.0 op_sel_hi:[1,0]
	v_mul_f32_e32 v38, v38, v82
	v_rcp_f32_e32 v80, v63
	v_pk_mul_f32 v[24:25], v[24:25], v[38:39]
	v_rcp_f32_e32 v82, v62
	v_mul_f32_e32 v39, v59, v80
	v_pk_mul_f32 v[20:21], v[20:21], v[36:37] op_sel_hi:[1,0]
	s_nop 1
	v_mov_b32_dpp v59, v20 row_ror:2 row_mask:0xf bank_mask:0xf
	s_nop 0
	v_mov_b32_dpp v63, v21 row_ror:2 row_mask:0xf bank_mask:0xf
	v_mov_b32_dpp v37, v20 row_ror:1 row_mask:0xf bank_mask:0xf
	v_mov_b32_dpp v56, v21 row_ror:1 row_mask:0xf bank_mask:0xf
	v_cndmask_b32_e64 v81, v100, v63, s[8:9]
	v_cndmask_b32_e64 v80, v94, v59, s[8:9]
	v_cndmask_b32_e64 v57, v56, v99, s[6:7]
	v_cndmask_b32_e64 v56, v37, v87, s[6:7]
	v_pk_fma_f32 v[80:81], v[72:73], v[80:81], v[76:77]
	v_pk_fma_f32 v[56:57], v[64:65], v[56:57], v[80:81]
	v_mul_f32_e32 v38, v58, v82
	v_pk_fma_f32 v[56:57], v[68:69], v[20:21], v[56:57]
	v_pk_mul_f32 v[38:39], v[60:61], v[38:39]
	v_mul_f32_e32 v37, 0xbfb8aa3b, v56
	v_exp_f32_e32 v80, v37
	v_mul_f32_e32 v37, 0xbfb8aa3b, v57
	v_exp_f32_e32 v81, v37
	s_nop 0
	v_pk_add_f32 v[58:59], v[80:81], 1.0 op_sel_hi:[1,0]
	s_nop 0
	v_rcp_f32_e32 v37, v59
	s_nop 0
	v_pk_mul_f32 v[22:23], v[22:23], v[36:37] op_sel_hi:[1,0]
	v_pk_mul_f32 v[18:19], v[18:19], v[36:37] op_sel_hi:[1,0]
	v_pk_mul_f32 v[16:17], v[16:17], v[36:37] op_sel_hi:[1,0]
	v_mul_f32_e32 v37, v57, v37
	v_mov_b32_dpp v62, v22 row_ror:2 row_mask:0xf bank_mask:0xf
	v_mov_b32_dpp v63, v23 row_ror:2 row_mask:0xf bank_mask:0xf
	v_mov_b32_dpp v59, v22 row_ror:1 row_mask:0xf bank_mask:0xf
	v_mov_b32_dpp v60, v23 row_ror:1 row_mask:0xf bank_mask:0xf
	v_cndmask_b32_e64 v63, v101, v63, s[8:9]
	v_cndmask_b32_e64 v62, v89, v62, s[8:9]
	v_cndmask_b32_e64 v61, v60, v93, s[6:7]
	v_cndmask_b32_e64 v60, v59, v88, s[6:7]
	v_pk_fma_f32 v[62:63], v[74:75], v[62:63], v[78:79]
	v_pk_fma_f32 v[60:61], v[66:67], v[60:61], v[62:63]
	v_rcp_f32_e32 v80, v58
	v_pk_fma_f32 v[60:61], v[70:71], v[22:23], v[60:61]
	v_mul_f32_e32 v59, 0xbfb8aa3b, v60
	v_exp_f32_e32 v62, v59
	v_mul_f32_e32 v59, 0xbfb8aa3b, v61
	v_exp_f32_e32 v63, v59
	s_nop 0
	v_pk_add_f32 v[62:63], v[62:63], 1.0 op_sel_hi:[1,0]
	v_rcp_f32_e32 v81, v63
	v_mul_f32_e32 v36, v56, v80
	v_pk_mul_f32 v[36:37], v[16:17], v[36:37]
	v_rcp_f32_e32 v56, v62
	v_mul_f32_e32 v17, v61, v81
	v_mul_f32_e32 v16, v60, v56
	v_pk_mul_f32 v[56:57], v[18:19], v[16:17]
	v_cvt_pk_bf16_f32 v16, v24, v25
	v_mad_i64_i32 v[24:25], s[16:17], v32, s33, v[128:129]
	v_cvt_pk_bf16_f32 v17, v38, v39
	v_cvt_pk_bf16_f32 v18, v36, v37
	v_cvt_pk_bf16_f32 v19, v56, v57
	v_lshl_add_u64 v[24:25], v[24:25], 0, v[130:131]
	global_store_dwordx4 v[24:25], v[16:19], off
	s_nop 1
	v_lshlrev_b64 v[16:17], 5, v[182:183]
	v_lshl_add_u64 v[24:25], s[46:47], 0, v[16:17]
	global_load_dwordx4 v[16:19], v[24:25], off
	global_load_dwordx4 v[36:39], v[24:25], off offset:16
	v_lshl_add_u64 v[24:25], s[76:77], 0, v[168:169]
	s_waitcnt vmcnt(1)
	v_mov_b32_e32 v56, v17
	v_mov_b32_e32 v57, v18
	v_mov_b32_e32 v17, v19
	v_pk_add_f32 v[16:17], v[56:57], v[16:17]
	s_waitcnt vmcnt(0)
	v_mov_b32_e32 v18, v38
	v_mov_b32_e32 v19, v36
	v_mov_b32_e32 v36, v39
	v_pk_add_f32 v[18:19], v[18:19], v[36:37]
	v_add_f32_e32 v16, v16, v17
	v_add_f32_e32 v16, v16, v19
	v_add_f32_e32 v16, v18, v16
	v_fmamk_f32 v16, v16, 0x3a000000, v178
	v_mad_u64_u32 v[18:19], s[16:17], v24, s97, 0
	s_nop 0
	v_rsq_f32_e32 v16, v16
	v_mad_i32_i24 v19, v25, s97, v19
	v_pk_mul_f32 v[14:15], v[14:15], v[16:17] op_sel_hi:[1,0]
	v_pk_mul_f32 v[12:13], v[12:13], v[16:17] op_sel_hi:[1,0]
	v_lshl_add_u64 v[18:19], s[52:53], 0, v[18:19]
	s_nop 0
	v_mov_b32_dpp v32, v12 row_ror:1 row_mask:0xf bank_mask:0xf
	v_mov_b32_dpp v35, v12 row_ror:2 row_mask:0xf bank_mask:0xf
	v_mov_b32_dpp v36, v13 row_ror:1 row_mask:0xf bank_mask:0xf
	v_mov_b32_dpp v37, v13 row_ror:2 row_mask:0xf bank_mask:0xf
	v_mov_b32_dpp v38, v14 row_ror:1 row_mask:0xf bank_mask:0xf
	v_mov_b32_dpp v39, v14 row_ror:2 row_mask:0xf bank_mask:0xf
	v_mov_b32_dpp v56, v15 row_ror:1 row_mask:0xf bank_mask:0xf
	v_mov_b32_dpp v57, v15 row_ror:2 row_mask:0xf bank_mask:0xf
	v_lshl_add_u64 v[24:25], v[180:181], 2, v[18:19]
	s_and_saveexec_b64 s[18:19], s[62:63]
	s_cbranch_execz .LBB0_801
	global_store_dwordx4 v[24:25], v[12:15], off
